# diff attention: next-unit K/V/Q/table loads issued before the combine; combine rewritten (chunked X exchange, sub-LN gains from LDS), table barrier merged
# speedup vs baseline: 1.0158x; 1.0158x over previous
; __device__ __forceinline__ int opaque_tid() { int t = (int)threadIdx.x; asm volatile("" : "+v"(t)); return t; }
; #define LAS __attribute__((address_space(3)))
; __device__ __forceinline__ int opaque_bx() { int b = (int)blockIdx.x; asm volatile("" : "+s"(b)); return b; }
; __device__ __forceinline__ KP kparams() { KP p = (KP)__builtin_amdgcn_kernarg_segment_ptr(); asm volatile("" : "+s"(p)); return p; }
; __device__ __forceinline__ void diff_phase(LAS unsigned char* lds, int L) {
;     constexpr int DKS = 18432, DVO = 2 * DKS, DST = DVO + 32768;
;     const KP P = kparams(); const int tid = opaque_tid(), lane = tid & 63, wave = __builtin_amdgcn_readfirstlane(tid >> 6);
;     const int r32 = lane & 31, hi = lane >> 5, map = wave >> 2, wq = wave & 3;
;     const int bx = opaque_bx(), vcu = (bx & 7) * 32 + (bx >> 3), xcd = vcu >> 5, grp = (vcu & 31) >> 3, mi = vcu & 7, eo = L >> 1;
;     unsigned char* ws = P->ws;
;     const bf16* Qb = (const bf16*)(ws + WS_Q); const bf16* Kb = (const bf16*)(ws + WS_K); const bf16* Vb = (const bf16*)(ws + WS_V); bf16* Ob = (bf16*)(ws + WS_O);
;     LAS float* dtab = (LAS float*)(lds + OFF_TAB);
;     const float lam_init = 0.8f - 0.6f * __builtin_amdgcn_exp2f(-0.3f * LOG2E * (float)L);
;     const float s1 = wave_sum(P->lq1[eo * 64 + lane] * P->lk1[eo * 64 + lane]), s2 = wave_sum(P->lq2[eo * 64 + lane] * P->lk2[eo * 64 + lane]);
;     const float lam = __builtin_amdgcn_exp2f(s1 * LOG2E) - __builtin_amdgcn_exp2f(s2 * LOG2E) + lam_init;
;     const int ksub = wave >> 2, krow0 = 32 * (wave & 3) + (lane >> 3);
;     const int klds = ksub * DKS + krow0 * 144 + (lane & 7) * 16;
;     const int vtile = wave >> 2, vdg = wave & 3, vkey0 = 64 * vtile + (lane >> 2);
;     const int vlds = DVO + vtile * 16384 + vdg * 4096 + 16 * lane;
;     ...
;             const float* sg = P->subln_g + eo * 128 + 4 * hi;
;             bf16* orow = Ob + (tokb + qw0 + r32) * 1024 + 128 * hj + 4 * hi;
;             f32x4 gv[16];
; #pragma unroll
;             for (int i = 0; i < 16; ++i) gv[i] = *(const f32x4*)(sg + 32 * (i >> 2) + 8 * (i & 3));
.LBB0_175:
	s_or_b64 exec, exec, s[38:39]
	s_andn2_b64 vcc, exec, s[36:37]
	s_mov_b64 s[4:5], -1
	s_waitcnt lgkmcnt(0)
	s_barrier
	s_cbranch_vccnz .LBB0_211
	s_mov_b64 s[8:9], s[60:61]
	v_mov_b32_e32 v3, v197
	s_mov_b32 s4, s57
	s_load_dwordx8 s[12:19], s[8:9], 0x58
	v_and_b32_e32 v6, 63, v3
	s_lshr_b32 s3, s78, 1
	v_lshl_or_b32 v0, s3, 6, v6
	v_mov_b32_e32 v1, v2
	v_lshlrev_b64 v[0:1], 2, v[0:1]
	s_waitcnt lgkmcnt(0)
	v_lshl_add_u64 v[4:5], s[12:13], 0, v[0:1]
	global_load_dword v7, v[4:5], off
	v_lshl_add_u64 v[4:5], s[14:15], 0, v[0:1]
	global_load_dword v8, v[4:5], off
	v_lshl_add_u64 v[4:5], s[16:17], 0, v[0:1]
	v_lshl_add_u64 v[0:1], s[18:19], 0, v[0:1]
	global_load_dword v4, v[4:5], off
	s_load_dwordx2 s[10:11], s[8:9], 0xb0
	global_load_dword v1, v[0:1], off
	v_readfirstlane_b32 s6, v3
	s_lshl_b32 s7, s4, 5
	s_ashr_i32 s21, s4, 3
	s_ashr_i32 s24, s6, 8
	s_bfe_u32 s26, s6, 0x20006
	s_and_b32 s7, s7, 0xe0
	s_bfe_u32 s36, s21, 0x20003
	s_and_b32 s37, s21, 7
	s_waitcnt lgkmcnt(0)
	s_add_u32 s12, s10, 0xa400000
	s_addc_u32 s13, s11, 0
	s_add_u32 s14, s10, 0xe400000
	s_addc_u32 s15, s11, 0
	s_add_u32 s16, s10, 0x12400000
	s_addc_u32 s17, s11, 0
	s_add_u32 s18, s10, 0x16400000
	v_bfe_u32 v11, v3, 3, 3
	v_bfe_u32 v13, v3, 2, 4
	s_addc_u32 s19, s11, 0
	s_lshl_b32 s39, s26, 5
	s_lshl_b32 s20, s24, 6
	v_or_b32_e32 v176, s39, v11
	v_or_b32_e32 v178, s20, v13
	v_sub_u32_e32 v14, 0xcf, v3
	v_cvt_f32_u32_e32 v5, s78
	v_and_b32_e32 v12, 7, v3
	v_cvt_f32_u32_e32 v17, v14
	s_mul_i32 s38, s24, 0x4800
	v_lshlrev_b32_e32 v16, 3, v12
	v_lshl_or_b32 v12, v12, 4, s38
	v_mad_u32_u24 v207, v176, s67, v12
	v_mul_f32_e32 v5, 0xbedd9914, v5
	v_mul_f32_e32 v17, 0x3d800000, v17
	v_exp_f32_e32 v5, v5
	v_log_f32_e32 v17, v17
	s_add_i32 s7, s7, s21
	v_mov_b32_e32 v9, 0x3f4ccccd
	s_ashr_i32 s7, s7, 1
	v_fmamk_f32 v5, v5, 0xbf19999a, v9
	v_mul_f32_e32 v9, 0x40aaaaab, v17
	s_xor_b32 s40, s37, 15
	s_ashr_i32 s21, s20, 31
	s_and_b32 s41, s7, -16
	v_cvt_i32_f32_e32 v9, v9
	s_cmpk_lt_u32 s6, 0x100
	s_cselect_b64 s[22:23], -1, 0
	s_lshl_b32 s6, s26, 14
	s_add_i32 s6, s6, 0
	v_lshlrev_b32_e32 v15, 4, v6
	s_cmp_eq_u32 s24, 1
	v_lshl_or_b32 v18, s24, 14, v15
	s_movk_i32 s7, 0xc0
	s_cselect_b64 s[24:25], -1, 0
	s_lshl_b32 s72, s3, 7
	s_movk_i32 s3, 0xff7f
	v_cmp_gt_u32_e32 vcc, s7, v3
	v_lshl_add_u32 v216, v6, 2, s6
	v_and_b32_e32 v177, 31, v3
	v_bfe_u32 v10, v3, 5, 1
	v_lshlrev_b32_e32 v0, 3, v3
	v_and_b32_e32 v181, 24, v0
	v_lshlrev_b32_e32 v211, 4, v10
	s_movk_i32 s5, 0x140
	v_lshlrev_b32_e32 v0, 3, v10
	v_ashrrev_i32_e32 v179, 31, v178
	v_readlane_b32 s1, v254, 0
	v_cmp_gt_i32_e64 s[4:5], s5, v3
	v_lshl_or_b32 v204, s26, 12, v18
	v_or_b32_e32 v205, s20, v16
	v_or_b32_e32 v206, s39, v181
	v_lshl_add_u32 v209, v3, 2, s1
	v_mul_u32_u24_e32 v210, 0x90, v177
	v_lshlrev_b32_e32 v213, 8, v10
	v_and_b32_e32 v214, 0xc0, v15
	v_sub_f32_e32 v217, 1.0, v5
	s_waitcnt vmcnt(0)
	v_mul_f32_e32 v11, v7, v8
	v_lshlrev_b32_e32 v180, 2, v10
	v_lshlrev_b32_e32 v182, 11, v176
	v_mov_b32_dpp v11, v11 quad_perm:[1,0,3,2] row_mask:0xf bank_mask:0xf bound_ctrl:1
	v_fmac_f32_e32 v11, v7, v8
	v_mul_f32_e32 v13, v4, v1
	v_mov_b32_e32 v183, v2
	v_lshlrev_b64 v[184:185], 11, v[178:179]
	v_mov_b32_dpp v13, v13 quad_perm:[1,0,3,2] row_mask:0xf bank_mask:0xf bound_ctrl:1
	v_fmac_f32_e32 v13, v4, v1
	v_add_f32_dpp v1, v11, v11 quad_perm:[2,3,0,1] row_mask:0xf bank_mask:0xf bound_ctrl:1
	s_mov_b32 s42, 0
	v_add_f32_dpp v4, v13, v13 quad_perm:[2,3,0,1] row_mask:0xf bank_mask:0xf bound_ctrl:1
	v_add_f32_dpp v1, v1, v1 row_half_mirror row_mask:0xf bank_mask:0xf bound_ctrl:1
	v_lshlrev_b32_e32 v186, 1, v0
	v_add_f32_dpp v4, v4, v4 row_half_mirror row_mask:0xf bank_mask:0xf bound_ctrl:1
	v_add_f32_dpp v1, v1, v1 row_mirror row_mask:0xf bank_mask:0xf bound_ctrl:1
	ds_swizzle_b32 v7, v1 offset:swizzle(SWAP,16)
	v_add_f32_dpp v4, v4, v4 row_mirror row_mask:0xf bank_mask:0xf bound_ctrl:1
	ds_swizzle_b32 v8, v4 offset:swizzle(SWAP,16)
	s_mov_b32 s43, 0
	s_waitcnt lgkmcnt(1)
	v_add_f32_e32 v1, v1, v7
	v_mov_b32_e32 v7, v1
	s_waitcnt lgkmcnt(0)
	v_add_f32_e32 v4, v4, v8
	v_mov_b32_e32 v8, v1
	v_mov_b32_e32 v11, v4
	v_mov_b32_e32 v12, v4
	v_permlane32_swap_b32_e32 v7, v8
	s_nop 0
	v_permlane32_swap_b32_e32 v11, v12
	v_xor_b32_e32 v7, v7, v8
	v_xor_b32_e32 v8, v11, v12
	v_xor_b32_e32 v7, v7, v1
	v_xor_b32_e32 v8, v8, v4
	v_add_f32_e32 v1, v1, v7
	v_add_f32_e32 v4, v4, v8
	v_mul_f32_e32 v1, 0x3fb8aa3b, v1
	v_mul_f32_e32 v4, 0x3fb8aa3b, v4
	v_exp_f32_e32 v1, v1
	v_exp_f32_e32 v4, v4
	v_min_i32_e32 v7, 15, v9
	v_sub_f32_e32 v1, v1, v4
	v_add_f32_e32 v1, v5, v1
	v_cndmask_b32_e64 v215, v1, 1.0, s[22:23]
	v_add_u32_e32 v1, 0xffffff30, v3
	v_add_u32_e32 v4, 16, v7
	v_cmp_lt_u32_e64 s[6:7], s3, v1
	s_movk_i32 s3, 0xcf
	v_cndmask_b32_e32 v4, v14, v4, vcc
	v_cmp_lt_i32_e32 vcc, s3, v3
	s_lshl_b32 s3, s36, 7
	s_add_i32 s27, s3, s20
	s_or_b32 s3, s3, s39
	v_lshlrev_b32_e32 v1, 2, v177
	v_or_b32_e32 v220, s3, v181
	v_sub_u32_e32 v1, v211, v1
	s_lshl_b32 s3, s26, 7
	v_lshlrev_b32_e32 v208, 3, v4
	v_lshlrev_b32_e32 v4, 1, v3
	v_subrev_u32_e32 v1, s3, v1
	v_and_b32_e32 v212, 32, v4
	v_cndmask_b32_e32 v218, 0, v249, vcc
	v_or_b32_e32 v219, s27, v16
	v_add_u32_e32 v221, 0, v1
	s_lshl_b64 s[26:27], s[72:73], 2
	s_load_dwordx2 s[44:45], s[8:9], 0x78
	v_cmp_gt_u32_e32 vcc, 0x80, v197
	s_waitcnt lgkmcnt(0)
	s_add_u32 s44, s44, s26
	s_addc_u32 s45, s45, s27
	s_and_saveexec_b64 s[46:47], vcc
	v_lshlrev_b32_e32 v0, 2, v197
	global_load_dword v1, v0, s[44:45]
	v_add_u32_e32 v0, 0x22580, v0
	s_waitcnt vmcnt(0)
	ds_write_b32 v0, v1
	s_or_b64 exec, exec, s[46:47]
	s_mov_b32 s100, 0
	s_branch .LBB0_178
; #define DF_LOAD(T) do { const bf16* kg = Kb + (tokb + 128 * (T) + krow0) * 1024 + kgcol; const bf16* vg = Vb + (tokb + 128 * (T) + vkey0) * 1024 + vgcol; \
;         _Pragma("unroll") for (int c_ = 0; c_ < 4; ++c_) { kreg[c_] = *(const u32x4*)(kg + c_ * 8 * 1024); vreg[c_] = *(const u32x4*)(vg + c_ * 16 * 1024); } } while (0)
; #define DF_STORE(sb) do { LAS unsigned char* s_ = lds + (sb) * DST; \
;         _Pragma("unroll") for (int c_ = 0; c_ < 4; ++c_) { *(LAS u32x4*)(s_ + klds + c_ * 8 * 144) = kreg[c_]; *(LAS u32x4*)(s_ + vlds + c_ * 1024) = vreg[c_]; } } while (0)
; __device__ __forceinline__ void diff_phase(LAS unsigned char* lds, int L) {
;     ...
;     for (int ui = 0; ui < 8; ++ui) {
;         const int bh = xcd * 16 + (ui >> 1) * 4 + grp, b = bh >> 3, hj = bh & 7, qblk = (ui & 1) ? mi : 15 - mi;
;         const size_t tokb = (size_t)b * SEQ;
;         const int kgcol = 128 * hj + 64 * ksub + 8 * (lane & 7), vgcol = 128 * hj + 32 * vdg + 8 * (lane & 3);
;         if (!(ui & 1)) {
;             if (tid < 320) { const int d = 207 - tid; float v = 0.f;
;                 if (d < 0) v = -INFINITY;
;                 else if (d < 128) { int bk = d;
;                     if (d >= 16) { bk = 16 + (int)(__builtin_amdgcn_logf((float)d * 0.0625f) * (16.0f / 3.0f)); bk = bk > 31 ? 31 : bk; }
;                     v = (P->rel_bias[bk * 8 + hj] - P->rel_bias[31 * 8 + hj]) * LOG2E; }
;                 dtab[tid] = v; }
;             __syncthreads();
;         }
;         const int q0 = 128 * qblk, NT = qblk + 1, qw0 = q0 + 32 * wq, th = (qw0 + 31) >> 6;
;         bf16x8 qr[4];
;         { const bf16* qp = Qb + (tokb + qw0 + r32) * 1024 + 128 * hj + 64 * map + 8 * hi;
; #pragma unroll
;           for (int d0 = 0; d0 < 4; ++d0) qr[d0] = *(const bf16x8*)(qp + 16 * d0); }
;         f32x16 o[4];
; #pragma unroll
;         for (int dg = 0; dg < 4; ++dg)
; #pragma unroll
;             for (int r = 0; r < 16; ++r) o[dg][r] = 0.f;
;         float m = 0.f, thr = -INFINITY, l = 0.f, R = 1.0f; f32x16 negm;
; #pragma unroll
;         for (int r = 0; r < 16; ++r) negm[r] = 0.f;
;         u32x4 kreg[4], vreg[4];
;     ...
;         DF_LOAD(NT - 1); DF_STORE(0);
;         __syncthreads();
;         asm volatile("" :: "v"(qr[0]), "v"(qr[1]), "v"(qr[2]), "v"(qr[3]));
.LBB0_178:
	s_lshl_b32 s44, s43, 1
	s_and_b32 s3, s44, 4
	s_or_b32 s3, s3, s36
	s_and_b32 s28, s43, 1
	s_cmp_eq_u32 s28, 0
	s_cselect_b64 s[30:31], -1, 0
	s_cmp_eq_u32 s28, 1
	s_cselect_b64 s[28:29], -1, 0
	s_and_b64 vcc, exec, s[28:29]
	s_cbranch_vccnz .LBB0_184
	s_and_saveexec_b64 s[28:29], s[4:5]
	s_cbranch_execz .Ldf_t1_skip
	s_and_saveexec_b64 s[34:35], s[6:7]
	s_cbranch_execz .Ldf_t1_in_skip
	s_load_dwordx2 s[46:47], s[8:9], 0x88
	v_or_b32_e32 v0, s3, v208
	v_ashrrev_i32_e32 v1, 31, v0
	s_lshl_b32 s45, s3, 2
	v_mov_b32_e32 v3, s45
	s_waitcnt lgkmcnt(0)
	v_lshl_add_u64 v[0:1], v[0:1], 2, s[46:47]
	global_load_dword v236, v[0:1], off
	s_nop 0
	global_load_dword v237, v3, s[46:47] offset:992
.Ldf_t1_in_skip:
	s_or_b64 exec, exec, s[34:35]
.Ldf_t1_skip:
	s_or_b64 exec, exec, s[28:29]
.LBB0_184:
	s_lshl_b32 s28, s42, 7
	s_and_b32 s45, s28, 0x200
	s_or_b32 s28, s44, s41
	s_ashr_i32 s28, s28, 3
	s_and_b64 s[30:31], s[30:31], exec
	s_cselect_b32 s35, s40, s37
	s_lshl_b32 s44, s35, 7
	s_ashr_i32 s29, s28, 31
	s_or_b32 s46, s44, s39
	s_lshl_b64 s[30:31], s[28:29], 11
	v_or_b32_e32 v1, s46, v177
	v_or_b32_e32 v4, s30, v1
	s_or_b32 s30, s30, s44
	s_lshl_b32 s34, s3, 7
	v_mov_b32_e32 v9, s31
	v_or_b32_e32 v8, s30, v176
	v_add_u32_e32 v0, s34, v205
	v_lshlrev_b64 v[8:9], 11, v[8:9]
	v_lshl_add_u64 v[8:9], s[14:15], 0, v[8:9]
	v_ashrrev_i32_e32 v1, 31, v0
	v_lshl_add_u64 v[0:1], v[0:1], 1, v[8:9]
	v_lshl_add_u64 v[8:9], s[30:31], 0, v[178:179]
	v_or_b32_e32 v3, s34, v206
	v_lshlrev_b64 v[8:9], 11, v[8:9]
	s_lshl_b32 s72, s3, 8
	v_lshl_add_u64 v[8:9], s[16:17], 0, v[8:9]
	v_lshlrev_b32_e32 v10, 1, v3
	v_mov_b32_e32 v11, v2
	s_movk_i32 s3, 0x4000
	v_lshl_add_u64 v[8:9], v[8:9], 0, v[10:11]
	v_add_co_u32_e32 v10, vcc, s3, v0
	global_load_dwordx4 v[128:131], v[0:1], off
	global_load_dwordx4 v[132:135], v[8:9], off
	v_addc_co_u32_e32 v11, vcc, 0, v1, vcc
	v_add_co_u32_e32 v12, vcc, s75, v8
	s_mov_b32 s3, 0x10000
	s_nop 0
	v_addc_co_u32_e32 v13, vcc, 0, v9, vcc
	global_load_dwordx4 v[140:143], v[10:11], off
	global_load_dwordx4 v[156:159], v[12:13], off
	v_add_co_u32_e32 v10, vcc, s75, v0
	v_mov_b32_e32 v5, s31
	s_nop 0
	v_addc_co_u32_e32 v11, vcc, 0, v1, vcc
	v_add_co_u32_e32 v12, vcc, s3, v8
	v_lshlrev_b64 v[6:7], 11, v[4:5]
	s_nop 0
	v_addc_co_u32_e32 v13, vcc, 0, v9, vcc
	s_mov_b32 s3, 0xc000
	v_lshl_add_u64 v[6:7], s[12:13], 0, v[6:7]
	v_add_co_u32_e32 v0, vcc, s3, v0
	v_lshl_add_u64 v[6:7], v[6:7], 0, s[72:73]
	global_load_dwordx4 v[160:163], v[10:11], off
	global_load_dwordx4 v[164:167], v[12:13], off
	v_addc_co_u32_e32 v1, vcc, 0, v1, vcc
	s_mov_b32 s3, 0x18000
	v_lshl_add_u64 v[6:7], s[20:21], 1, v[6:7]
	v_mov_b32_e32 v187, v2
	v_add_co_u32_e32 v8, vcc, s3, v8
	v_lshl_add_u64 v[6:7], v[6:7], 0, v[186:187]
	s_nop 0
	v_addc_co_u32_e32 v9, vcc, 0, v9, vcc
	global_load_dwordx4 v[168:171], v[0:1], off
	global_load_dwordx4 v[172:175], v[8:9], off
	global_load_dwordx4 v[136:139], v[6:7], off
	global_load_dwordx4 v[144:147], v[6:7], off offset:32
	global_load_dwordx4 v[148:151], v[6:7], off offset:64
	global_load_dwordx4 v[152:155], v[6:7], off offset:96
	s_cmp_lg_u32 s100, 0
	s_cbranch_scc1 .Ldf_c1
.Ldf_p2:
	s_bitcmp1_b32 s43, 0
	s_cbranch_scc1 .Ldf_p2_notab
	s_and_saveexec_b64 s[30:31], s[4:5]
	s_cbranch_execz .Ldf_t2_skip
	v_mov_b32_e32 v0, v218
	s_and_saveexec_b64 s[48:49], s[6:7]
	s_cbranch_execz .Ldf_t2_in_skip
	s_waitcnt vmcnt(12)
	v_sub_f32_e32 v0, v236, v237
	v_mul_f32_e32 v0, 0x3fb8aa3b, v0
.Ldf_t2_in_skip:
	s_or_b64 exec, exec, s[48:49]
	ds_write_b32 v209, v0
.Ldf_t2_skip:
	s_or_b64 exec, exec, s[30:31]
.Ldf_p2_notab:
	v_add_u32_e32 v6, s45, v219
	v_or_b32_e32 v0, s45, v220
	s_lshl_b32 s49, s35, 9
	s_lshl_b64 s[28:29], s[28:29], 22
	s_lshl_b32 s3, s35, 18
	v_mov_b32_e32 v1, v2
	v_add_u32_e32 v3, 0, v207
	v_add_u32_e32 v8, 0, v204
	v_ashrrev_i32_e32 v7, 31, v6
	v_lshlrev_b32_e32 v0, 1, v0
	s_lshr_b32 s48, s46, 6
	s_addk_i32 s49, 0x200
	s_or_b32 s3, s28, s3
	v_mov_b32_e32 v14, v2
	v_mov_b32_e32 v15, v2
	v_lshl_add_u64 v[190:191], v[6:7], 1, v[182:183]
	v_lshl_add_u64 v[192:193], v[184:185], 0, v[0:1]
	v_lshlrev_b64 v[188:189], 10, v[4:5]
	s_add_u32 s28, s10, s3
	v_mov_b32_e32 v0, v2
	v_mov_b32_e32 v4, v2
	v_mov_b32_e32 v5, v2
	v_mov_b32_e32 v6, v2
	v_mov_b32_e32 v7, v2
	v_mov_b32_e32 v9, v2
	v_mov_b32_e32 v10, v2
	v_mov_b32_e32 v11, v2
	v_mov_b32_e32 v12, v2
	v_mov_b32_e32 v13, v2
	s_mov_b32 s47, 0
	s_addc_u32 s29, s11, s29
	s_lshl_b32 s50, s35, 1
	s_add_i32 s51, s44, 0xf0
	s_mov_b32 s53, 0xff800000
	s_waitcnt vmcnt(11)
	ds_write_b128 v3, v[128:131]
	s_waitcnt vmcnt(10)
	ds_write_b128 v8, v[132:135] offset:36864
	s_waitcnt vmcnt(9)
	ds_write_b128 v3, v[140:143] offset:1152
	s_waitcnt vmcnt(8)
	ds_write_b128 v8, v[156:159] offset:37888
	s_waitcnt vmcnt(7)
	ds_write_b128 v3, v[160:163] offset:2304
	s_waitcnt vmcnt(6)
	ds_write_b128 v8, v[164:167] offset:38912
	s_waitcnt vmcnt(5)
	ds_write_b128 v3, v[168:171] offset:3456
	s_waitcnt vmcnt(4)
	ds_write_b128 v8, v[172:175] offset:39936
	v_mov_b32_e32 v3, v2
	v_mov_b32_e32 v8, v2
	v_mov_b64_e32 v[78:79], v[14:15]
	v_mov_b64_e32 v[62:63], v[14:15]
	v_mov_b64_e32 v[46:47], v[14:15]
	v_mov_b64_e32 v[30:31], v[14:15]
	v_mov_b64_e32 v[94:95], v[14:15]
	v_mov_b32_e32 v187, 0
	v_mov_b64_e32 v[76:77], v[12:13]
	v_mov_b64_e32 v[74:75], v[10:11]
	v_mov_b64_e32 v[72:73], v[8:9]
	v_mov_b64_e32 v[70:71], v[6:7]
	v_mov_b64_e32 v[68:69], v[4:5]
	v_mov_b64_e32 v[66:67], v[2:3]
	v_mov_b64_e32 v[64:65], v[0:1]
	v_mov_b64_e32 v[60:61], v[12:13]
	v_mov_b64_e32 v[58:59], v[10:11]
	v_mov_b64_e32 v[56:57], v[8:9]
	v_mov_b64_e32 v[54:55], v[6:7]
	v_mov_b64_e32 v[52:53], v[4:5]
	v_mov_b64_e32 v[50:51], v[2:3]
	v_mov_b64_e32 v[48:49], v[0:1]
	v_mov_b64_e32 v[44:45], v[12:13]
	v_mov_b64_e32 v[42:43], v[10:11]
	v_mov_b64_e32 v[40:41], v[8:9]
	v_mov_b64_e32 v[38:39], v[6:7]
	v_mov_b64_e32 v[36:37], v[4:5]
	v_mov_b64_e32 v[34:35], v[2:3]
	v_mov_b64_e32 v[32:33], v[0:1]
	v_mov_b64_e32 v[28:29], v[12:13]
	v_mov_b64_e32 v[26:27], v[10:11]
	v_mov_b64_e32 v[24:25], v[8:9]
	v_mov_b64_e32 v[22:23], v[6:7]
	v_mov_b64_e32 v[20:21], v[4:5]
	v_mov_b64_e32 v[18:19], v[2:3]
	v_mov_b64_e32 v[16:17], v[0:1]
	s_mov_b32 s52, 0
	v_mov_b64_e32 v[92:93], v[12:13]
	v_mov_b64_e32 v[90:91], v[10:11]
	v_mov_b64_e32 v[88:89], v[8:9]
	v_mov_b64_e32 v[86:87], v[6:7]
	v_mov_b64_e32 v[84:85], v[4:5]
	v_mov_b64_e32 v[82:83], v[2:3]
	v_mov_b64_e32 v[80:81], v[0:1]
	v_mov_b32_e32 v3, 0
	s_waitcnt lgkmcnt(0)
	s_barrier
	s_waitcnt vmcnt(0)
	s_branch .LBB0_186

; #define LAS __attribute__((address_space(3)))
; __device__ __forceinline__ void diff_phase(LAS unsigned char* lds, int L) {
;     ...
;         const float lt = l + xlane_partner(l); const float f = (map ? lam : 1.0f) / lt;
;         LAS float* X = (LAS float*)(lds + wq * 16384);
;         if (map == 1) {
; #pragma unroll
;             for (int dg = 0; dg < 4; ++dg)
; #pragma unroll
;                 for (int r = 0; r < 16; ++r) X[(dg * 16 + r) * 64 + lane] = o[dg][r] * f;
.LBB0_206:
	v_mov_b32_e32 v0, v3
	v_mov_b32_e32 v1, v3
	s_nop 1
	v_permlane32_swap_b32_e32 v0, v1
	v_xor_b32_e32 v0, v1, v0
	v_xor_b32_e32 v0, v0, v3
	v_add_f32_e32 v0, v3, v0
	v_div_scale_f32 v1, s[28:29], v0, v0, v215
	v_rcp_f32_e32 v3, v1
	s_nop 0
	v_fma_f32 v4, -v1, v3, 1.0
	v_fmac_f32_e32 v3, v4, v3
	v_div_scale_f32 v4, vcc, v215, v0, v215
	v_mul_f32_e32 v5, v4, v3
	v_fma_f32 v6, -v1, v5, v4
	v_fmac_f32_e32 v5, v6, v3
	v_fma_f32 v1, -v1, v5, v4
	v_div_fmas_f32 v1, v1, v3, v5
	v_div_fixup_f32 v0, v1, v0, v215
	v_mov_b32_e32 v238, v0
	v_lshl_add_u64 v[240:241], v[188:189], 1, s[18:19]
	s_lshl_b32 s72, s34, 1
	v_lshlrev_b32_e32 v242, 1, v180
	v_mov_b32_e32 v243, v2
	v_lshl_add_u64 v[240:241], v[240:241], 0, s[72:73]
	v_lshl_add_u64 v[240:241], v[240:241], 0, v[242:243]
	s_add_i32 s43, s43, 1
	s_add_i32 s42, s42, 2
	s_cmp_eq_u32 s43, 8
	s_cbranch_scc1 .Ldf_c1
	s_mov_b32 s100, 1
	s_branch .LBB0_178
.Ldf_c1:
	s_andn2_b64 vcc, exec, s[24:25]
	s_cbranch_vccnz .Ldf_c1_done
	v_mul_f32_e32 v1, v64, v238
	v_mul_f32_e32 v3, v65, v238
	ds_write2st64_b32 v216, v1, v3 offset1:1
	v_mul_f32_e32 v1, v66, v238
	v_mul_f32_e32 v3, v67, v238
	ds_write2st64_b32 v216, v1, v3 offset0:2 offset1:3
	v_mul_f32_e32 v1, v68, v238
	v_mul_f32_e32 v3, v69, v238
	ds_write2st64_b32 v216, v1, v3 offset0:4 offset1:5
	v_mul_f32_e32 v1, v70, v238
	v_mul_f32_e32 v3, v71, v238
	ds_write2st64_b32 v216, v1, v3 offset0:6 offset1:7
	v_mul_f32_e32 v1, v72, v238
	v_mul_f32_e32 v3, v73, v238
	ds_write2st64_b32 v216, v1, v3 offset0:8 offset1:9
	v_mul_f32_e32 v1, v74, v238
	v_mul_f32_e32 v3, v75, v238
	ds_write2st64_b32 v216, v1, v3 offset0:10 offset1:11
	v_mul_f32_e32 v1, v76, v238
	v_mul_f32_e32 v3, v77, v238
	ds_write2st64_b32 v216, v1, v3 offset0:12 offset1:13
	v_mul_f32_e32 v1, v78, v238
	v_mul_f32_e32 v3, v79, v238
	ds_write2st64_b32 v216, v1, v3 offset0:14 offset1:15
	v_mul_f32_e32 v1, v48, v238
	v_mul_f32_e32 v3, v49, v238
	ds_write2st64_b32 v216, v1, v3 offset0:16 offset1:17
	v_mul_f32_e32 v1, v50, v238
	v_mul_f32_e32 v3, v51, v238
	ds_write2st64_b32 v216, v1, v3 offset0:18 offset1:19
	v_mul_f32_e32 v1, v52, v238
	v_mul_f32_e32 v3, v53, v238
	ds_write2st64_b32 v216, v1, v3 offset0:20 offset1:21
	v_mul_f32_e32 v1, v54, v238
	v_mul_f32_e32 v3, v55, v238
	ds_write2st64_b32 v216, v1, v3 offset0:22 offset1:23
	v_mul_f32_e32 v1, v56, v238
	v_mul_f32_e32 v3, v57, v238
	ds_write2st64_b32 v216, v1, v3 offset0:24 offset1:25
	v_mul_f32_e32 v1, v58, v238
	v_mul_f32_e32 v3, v59, v238
	ds_write2st64_b32 v216, v1, v3 offset0:26 offset1:27
	v_mul_f32_e32 v1, v60, v238
	v_mul_f32_e32 v3, v61, v238
	ds_write2st64_b32 v216, v1, v3 offset0:28 offset1:29
	v_mul_f32_e32 v1, v62, v238
	v_mul_f32_e32 v3, v63, v238
	ds_write2st64_b32 v216, v1, v3 offset0:30 offset1:31
	v_mul_f32_e32 v1, v32, v238
	v_mul_f32_e32 v3, v33, v238
	ds_write2st64_b32 v216, v1, v3 offset0:32 offset1:33
	v_mul_f32_e32 v1, v34, v238
	v_mul_f32_e32 v3, v35, v238
	ds_write2st64_b32 v216, v1, v3 offset0:34 offset1:35
	v_mul_f32_e32 v1, v36, v238
	v_mul_f32_e32 v3, v37, v238
	ds_write2st64_b32 v216, v1, v3 offset0:36 offset1:37
	v_mul_f32_e32 v1, v38, v238
	v_mul_f32_e32 v3, v39, v238
	ds_write2st64_b32 v216, v1, v3 offset0:38 offset1:39
	v_mul_f32_e32 v1, v40, v238
	v_mul_f32_e32 v3, v41, v238
	ds_write2st64_b32 v216, v1, v3 offset0:40 offset1:41
	v_mul_f32_e32 v1, v42, v238
	v_mul_f32_e32 v3, v43, v238
	ds_write2st64_b32 v216, v1, v3 offset0:42 offset1:43
	v_mul_f32_e32 v1, v44, v238
	v_mul_f32_e32 v3, v45, v238
	ds_write2st64_b32 v216, v1, v3 offset0:44 offset1:45
	v_mul_f32_e32 v1, v46, v238
	v_mul_f32_e32 v3, v47, v238
	ds_write2st64_b32 v216, v1, v3 offset0:46 offset1:47
	v_mul_f32_e32 v1, v16, v238
	v_mul_f32_e32 v3, v17, v238
	ds_write2st64_b32 v216, v1, v3 offset0:48 offset1:49
	v_mul_f32_e32 v1, v18, v238
	v_mul_f32_e32 v3, v19, v238
	ds_write2st64_b32 v216, v1, v3 offset0:50 offset1:51
	v_mul_f32_e32 v1, v20, v238
	v_mul_f32_e32 v3, v21, v238
	ds_write2st64_b32 v216, v1, v3 offset0:52 offset1:53
	v_mul_f32_e32 v1, v22, v238
	v_mul_f32_e32 v3, v23, v238
	ds_write2st64_b32 v216, v1, v3 offset0:54 offset1:55
	v_mul_f32_e32 v1, v24, v238
	v_mul_f32_e32 v3, v25, v238
	ds_write2st64_b32 v216, v1, v3 offset0:56 offset1:57
	v_mul_f32_e32 v1, v26, v238
	v_mul_f32_e32 v3, v27, v238
	ds_write2st64_b32 v216, v1, v3 offset0:58 offset1:59
	v_mul_f32_e32 v1, v28, v238
	v_mul_f32_e32 v3, v29, v238
	ds_write2st64_b32 v216, v1, v3 offset0:60 offset1:61
	v_mul_f32_e32 v1, v30, v238
	v_mul_f32_e32 v3, v31, v238
	ds_write2st64_b32 v216, v1, v3 offset0:62 offset1:63
; __device__ __forceinline__ void diff_phase(LAS unsigned char* lds, int L) {
;     ...
;         __syncthreads();
;         if (map == 0) {
;             float ss = 0.f;
; #pragma unroll
;             for (int dg = 0; dg < 4; ++dg)
; #pragma unroll
;                 for (int r = 0; r < 16; ++r) { const float d = o[dg][r] * f - X[(dg * 16 + r) * 64 + lane]; o[dg][r] = d; ss += d * d; }
;             ss += xlane_partner(ss);
;             const float rn = rsqrtf(ss * (1.0f / 128.0f) + RMS_EPS) * (1.0f - lam_init);
.Ldf_c1_done:
	s_waitcnt lgkmcnt(0)
	s_barrier
	s_andn2_b64 vcc, exec, s[22:23]
	s_cbranch_vccnz .Ldf_c2_done
	ds_read2st64_b32 v[80:81], v216 offset1:1
	ds_read2st64_b32 v[82:83], v216 offset0:2 offset1:3
	ds_read2st64_b32 v[84:85], v216 offset0:4 offset1:5
	ds_read2st64_b32 v[86:87], v216 offset0:6 offset1:7
	ds_read2st64_b32 v[88:89], v216 offset0:8 offset1:9
	ds_read2st64_b32 v[90:91], v216 offset0:10 offset1:11
	ds_read2st64_b32 v[92:93], v216 offset0:12 offset1:13
	ds_read2st64_b32 v[94:95], v216 offset0:14 offset1:15
	ds_read2st64_b32 v[96:97], v216 offset0:16 offset1:17
	ds_read2st64_b32 v[98:99], v216 offset0:18 offset1:19
	ds_read2st64_b32 v[100:101], v216 offset0:20 offset1:21
	ds_read2st64_b32 v[102:103], v216 offset0:22 offset1:23
	ds_read2st64_b32 v[104:105], v216 offset0:24 offset1:25
	ds_read2st64_b32 v[106:107], v216 offset0:26 offset1:27
	ds_read2st64_b32 v[108:109], v216 offset0:28 offset1:29
	ds_read2st64_b32 v[110:111], v216 offset0:30 offset1:31
	v_lshlrev_b32_e32 v7, 2, v180
	v_add_u32_e32 v7, 0x22580, v7
	s_waitcnt lgkmcnt(8)
	v_fma_f32 v64, v64, v238, -v80
	v_fma_f32 v65, v65, v238, -v81
	v_fma_f32 v66, v66, v238, -v82
	v_fma_f32 v67, v67, v238, -v83
	v_fma_f32 v68, v68, v238, -v84
	v_fma_f32 v69, v69, v238, -v85
	v_fma_f32 v70, v70, v238, -v86
	v_fma_f32 v71, v71, v238, -v87
	v_fma_f32 v72, v72, v238, -v88
	v_fma_f32 v73, v73, v238, -v89
	v_fma_f32 v74, v74, v238, -v90
	v_fma_f32 v75, v75, v238, -v91
	v_fma_f32 v76, v76, v238, -v92
	v_fma_f32 v77, v77, v238, -v93
	v_fma_f32 v78, v78, v238, -v94
	v_fma_f32 v79, v79, v238, -v95
	v_mul_f32_e32 v0, v64, v64
	v_mul_f32_e32 v1, v65, v65
	v_mul_f32_e32 v3, v66, v66
	v_mul_f32_e32 v6, v67, v67
	v_fmac_f32_e32 v0, v68, v68
	v_fmac_f32_e32 v1, v69, v69
	v_fmac_f32_e32 v3, v70, v70
	v_fmac_f32_e32 v6, v71, v71
	v_fmac_f32_e32 v0, v72, v72
	v_fmac_f32_e32 v1, v73, v73
	v_fmac_f32_e32 v3, v74, v74
	v_fmac_f32_e32 v6, v75, v75
	v_fmac_f32_e32 v0, v76, v76
	v_fmac_f32_e32 v1, v77, v77
	v_fmac_f32_e32 v3, v78, v78
	v_fmac_f32_e32 v6, v79, v79
	ds_read2st64_b32 v[112:113], v216 offset0:32 offset1:33
	ds_read2st64_b32 v[114:115], v216 offset0:34 offset1:35
	ds_read2st64_b32 v[116:117], v216 offset0:36 offset1:37
	ds_read2st64_b32 v[118:119], v216 offset0:38 offset1:39
	ds_read2st64_b32 v[120:121], v216 offset0:40 offset1:41
	ds_read2st64_b32 v[122:123], v216 offset0:42 offset1:43
	ds_read2st64_b32 v[124:125], v216 offset0:44 offset1:45
	ds_read2st64_b32 v[126:127], v216 offset0:46 offset1:47
	s_waitcnt lgkmcnt(8)
	v_fma_f32 v48, v48, v238, -v96
	v_fma_f32 v49, v49, v238, -v97
	v_fma_f32 v50, v50, v238, -v98
	v_fma_f32 v51, v51, v238, -v99
	v_fma_f32 v52, v52, v238, -v100
	v_fma_f32 v53, v53, v238, -v101
	v_fma_f32 v54, v54, v238, -v102
	v_fma_f32 v55, v55, v238, -v103
	v_fma_f32 v56, v56, v238, -v104
	v_fma_f32 v57, v57, v238, -v105
	v_fma_f32 v58, v58, v238, -v106
	v_fma_f32 v59, v59, v238, -v107
	v_fma_f32 v60, v60, v238, -v108
	v_fma_f32 v61, v61, v238, -v109
	v_fma_f32 v62, v62, v238, -v110
	v_fma_f32 v63, v63, v238, -v111
	v_fmac_f32_e32 v0, v48, v48
	v_fmac_f32_e32 v1, v49, v49
	v_fmac_f32_e32 v3, v50, v50
	v_fmac_f32_e32 v6, v51, v51
	v_fmac_f32_e32 v0, v52, v52
	v_fmac_f32_e32 v1, v53, v53
	v_fmac_f32_e32 v3, v54, v54
	v_fmac_f32_e32 v6, v55, v55
	v_fmac_f32_e32 v0, v56, v56
	v_fmac_f32_e32 v1, v57, v57
	v_fmac_f32_e32 v3, v58, v58
	v_fmac_f32_e32 v6, v59, v59
	v_fmac_f32_e32 v0, v60, v60
	v_fmac_f32_e32 v1, v61, v61
	v_fmac_f32_e32 v3, v62, v62
	v_fmac_f32_e32 v6, v63, v63
	ds_read2st64_b32 v[80:81], v216 offset0:48 offset1:49
	ds_read2st64_b32 v[82:83], v216 offset0:50 offset1:51
	ds_read2st64_b32 v[84:85], v216 offset0:52 offset1:53
	ds_read2st64_b32 v[86:87], v216 offset0:54 offset1:55
	ds_read2st64_b32 v[88:89], v216 offset0:56 offset1:57
	ds_read2st64_b32 v[90:91], v216 offset0:58 offset1:59
	ds_read2st64_b32 v[92:93], v216 offset0:60 offset1:61
	ds_read2st64_b32 v[94:95], v216 offset0:62 offset1:63
	s_waitcnt lgkmcnt(8)
	v_fma_f32 v32, v32, v238, -v112
	v_fma_f32 v33, v33, v238, -v113
	v_fma_f32 v34, v34, v238, -v114
	v_fma_f32 v35, v35, v238, -v115
	v_fma_f32 v36, v36, v238, -v116
	v_fma_f32 v37, v37, v238, -v117
	v_fma_f32 v38, v38, v238, -v118
	v_fma_f32 v39, v39, v238, -v119
	v_fma_f32 v40, v40, v238, -v120
	v_fma_f32 v41, v41, v238, -v121
	v_fma_f32 v42, v42, v238, -v122
	v_fma_f32 v43, v43, v238, -v123
	v_fma_f32 v44, v44, v238, -v124
	v_fma_f32 v45, v45, v238, -v125
	v_fma_f32 v46, v46, v238, -v126
	v_fma_f32 v47, v47, v238, -v127
	v_fmac_f32_e32 v0, v32, v32
	v_fmac_f32_e32 v1, v33, v33
	v_fmac_f32_e32 v3, v34, v34
	v_fmac_f32_e32 v6, v35, v35
	v_fmac_f32_e32 v0, v36, v36
	v_fmac_f32_e32 v1, v37, v37
	v_fmac_f32_e32 v3, v38, v38
	v_fmac_f32_e32 v6, v39, v39
	v_fmac_f32_e32 v0, v40, v40
	v_fmac_f32_e32 v1, v41, v41
	v_fmac_f32_e32 v3, v42, v42
	v_fmac_f32_e32 v6, v43, v43
	v_fmac_f32_e32 v0, v44, v44
	v_fmac_f32_e32 v1, v45, v45
	v_fmac_f32_e32 v3, v46, v46
	v_fmac_f32_e32 v6, v47, v47
	s_waitcnt lgkmcnt(0)
; __device__ __forceinline__ unsigned cvtpk(float lo, float hi) { f32x2 v = {lo, hi}; bf16x2_t b = __builtin_convertvector(v, bf16x2_t); return __builtin_bit_cast(unsigned, b); }
; __device__ __forceinline__ void diff_phase(LAS unsigned char* lds, int L) {
;     ...
;                 for (int r = 0; r < 16; ++r) { const float d = o[dg][r] * f - X[(dg * 16 + r) * 64 + lane]; o[dg][r] = d; ss += d * d; }
;             ss += xlane_partner(ss);
;             const float rn = rsqrtf(ss * (1.0f / 128.0f) + RMS_EPS) * (1.0f - lam_init);
;             const float* sg = P->subln_g + eo * 128 + 4 * hi;
;             bf16* orow = Ob + (tokb + qw0 + r32) * 1024 + 128 * hj + 4 * hi;
;             f32x4 gv[16];
; #pragma unroll
;             for (int i = 0; i < 16; ++i) gv[i] = *(const f32x4*)(sg + 32 * (i >> 2) + 8 * (i & 3));
; #pragma unroll
;             for (int dg = 0; dg < 4; ++dg)
; #pragma unroll
;                 for (int g = 0; g < 4; ++g) { const f32x4 gg = gv[4 * dg + g];
;                     u32x2 w; w.x = cvtpk(o[dg][4 * g] * rn * gg[0], o[dg][4 * g + 1] * rn * gg[1]); w.y = cvtpk(o[dg][4 * g + 2] * rn * gg[2], o[dg][4 * g + 3] * rn * gg[3]);
;                     *(u32x2*)(orow + 32 * dg + 8 * g) = w; }
	v_fma_f32 v16, v16, v238, -v80
	v_fma_f32 v17, v17, v238, -v81
	v_fma_f32 v18, v18, v238, -v82
	v_fma_f32 v19, v19, v238, -v83
	v_fma_f32 v20, v20, v238, -v84
	v_fma_f32 v21, v21, v238, -v85
	v_fma_f32 v22, v22, v238, -v86
	v_fma_f32 v23, v23, v238, -v87
	v_fma_f32 v24, v24, v238, -v88
	v_fma_f32 v25, v25, v238, -v89
	v_fma_f32 v26, v26, v238, -v90
	v_fma_f32 v27, v27, v238, -v91
	v_fma_f32 v28, v28, v238, -v92
	v_fma_f32 v29, v29, v238, -v93
	v_fma_f32 v30, v30, v238, -v94
	v_fma_f32 v31, v31, v238, -v95
	v_fmac_f32_e32 v0, v16, v16
	v_fmac_f32_e32 v1, v17, v17
	v_fmac_f32_e32 v3, v18, v18
	v_fmac_f32_e32 v6, v19, v19
	v_fmac_f32_e32 v0, v20, v20
	v_fmac_f32_e32 v1, v21, v21
	v_fmac_f32_e32 v3, v22, v22
	v_fmac_f32_e32 v6, v23, v23
	v_fmac_f32_e32 v0, v24, v24
	v_fmac_f32_e32 v1, v25, v25
	v_fmac_f32_e32 v3, v26, v26
	v_fmac_f32_e32 v6, v27, v27
	v_fmac_f32_e32 v0, v28, v28
	v_fmac_f32_e32 v1, v29, v29
	v_fmac_f32_e32 v3, v30, v30
	v_fmac_f32_e32 v6, v31, v31
	ds_read_b128 v[96:99], v7 offset:0
	ds_read_b128 v[100:103], v7 offset:32
	ds_read_b128 v[104:107], v7 offset:64
	ds_read_b128 v[108:111], v7 offset:96
	ds_read_b128 v[80:83], v7 offset:128
	ds_read_b128 v[84:87], v7 offset:160
	ds_read_b128 v[88:91], v7 offset:192
	ds_read_b128 v[92:95], v7 offset:224
	v_add_f32_e32 v0, v0, v1
	v_add_f32_e32 v3, v3, v6
	v_add_f32_e32 v0, v0, v3
	v_mov_b32_e32 v8, v0
	v_mov_b32_e32 v9, v0
	s_nop 1
	v_permlane32_swap_b32_e32 v8, v9
	v_xor_b32_e32 v8, v8, v9
	v_xor_b32_e32 v8, v8, v0
	v_add_f32_e32 v0, v0, v8
	v_fmamk_f32 v0, v0, 0x3c000000, v196
	v_mul_f32_e32 v8, 0x4b800000, v0
	v_cmp_gt_f32_e32 vcc, s79, v0
	s_nop 1
	v_cndmask_b32_e32 v0, v0, v8, vcc
	v_rsq_f32_e32 v0, v0
	s_nop 0
	v_mul_f32_e32 v8, 0x45800000, v0
	v_cndmask_b32_e32 v0, v0, v8, vcc
	v_mul_f32_e32 v0, v217, v0
	s_waitcnt lgkmcnt(4)
	v_pk_mul_f32 v[112:113], v[64:65], v[0:1] op_sel_hi:[1,0]
	v_pk_mul_f32 v[114:115], v[66:67], v[0:1] op_sel_hi:[1,0]
	v_pk_mul_f32 v[112:113], v[96:97], v[112:113]
	v_pk_mul_f32 v[114:115], v[98:99], v[114:115]
	v_cvt_pk_bf16_f32 v112, v112, v113
	v_cvt_pk_bf16_f32 v113, v114, v115
	global_store_dwordx2 v[240:241], v[112:113], off
	v_pk_mul_f32 v[116:117], v[68:69], v[0:1] op_sel_hi:[1,0]
	v_pk_mul_f32 v[118:119], v[70:71], v[0:1] op_sel_hi:[1,0]
	v_pk_mul_f32 v[116:117], v[100:101], v[116:117]
	v_pk_mul_f32 v[118:119], v[102:103], v[118:119]
	v_cvt_pk_bf16_f32 v116, v116, v117
	v_cvt_pk_bf16_f32 v117, v118, v119
	global_store_dwordx2 v[240:241], v[116:117], off offset:16
	v_pk_mul_f32 v[120:121], v[72:73], v[0:1] op_sel_hi:[1,0]
	v_pk_mul_f32 v[122:123], v[74:75], v[0:1] op_sel_hi:[1,0]
	v_pk_mul_f32 v[120:121], v[104:105], v[120:121]
	v_pk_mul_f32 v[122:123], v[106:107], v[122:123]
	v_cvt_pk_bf16_f32 v120, v120, v121
	v_cvt_pk_bf16_f32 v121, v122, v123
	global_store_dwordx2 v[240:241], v[120:121], off offset:32
	v_pk_mul_f32 v[124:125], v[76:77], v[0:1] op_sel_hi:[1,0]
	v_pk_mul_f32 v[126:127], v[78:79], v[0:1] op_sel_hi:[1,0]
	v_pk_mul_f32 v[124:125], v[108:109], v[124:125]
	v_pk_mul_f32 v[126:127], v[110:111], v[126:127]
	v_cvt_pk_bf16_f32 v124, v124, v125
	v_cvt_pk_bf16_f32 v125, v126, v127
	global_store_dwordx2 v[240:241], v[124:125], off offset:48
	ds_read_b128 v[96:99], v7 offset:256
	ds_read_b128 v[100:103], v7 offset:288
	ds_read_b128 v[104:107], v7 offset:320
	ds_read_b128 v[108:111], v7 offset:352
	s_waitcnt lgkmcnt(4)
; __device__ __forceinline__ unsigned cvtpk(float lo, float hi) { f32x2 v = {lo, hi}; bf16x2_t b = __builtin_convertvector(v, bf16x2_t); return __builtin_bit_cast(unsigned, b); }
; __device__ __forceinline__ void diff_phase(LAS unsigned char* lds, int L) {
;     ...
; #pragma unroll
;             for (int i = 0; i < 16; ++i) gv[i] = *(const f32x4*)(sg + 32 * (i >> 2) + 8 * (i & 3));
; #pragma unroll
;             for (int dg = 0; dg < 4; ++dg)
; #pragma unroll
;                 for (int g = 0; g < 4; ++g) { const f32x4 gg = gv[4 * dg + g];
;                     u32x2 w; w.x = cvtpk(o[dg][4 * g] * rn * gg[0], o[dg][4 * g + 1] * rn * gg[1]); w.y = cvtpk(o[dg][4 * g + 2] * rn * gg[2], o[dg][4 * g + 3] * rn * gg[3]);
;                     *(u32x2*)(orow + 32 * dg + 8 * g) = w; }
;         }
;         __syncthreads();
	v_pk_mul_f32 v[112:113], v[48:49], v[0:1] op_sel_hi:[1,0]
	v_pk_mul_f32 v[114:115], v[50:51], v[0:1] op_sel_hi:[1,0]
	v_pk_mul_f32 v[112:113], v[80:81], v[112:113]
	v_pk_mul_f32 v[114:115], v[82:83], v[114:115]
	v_cvt_pk_bf16_f32 v112, v112, v113
	v_cvt_pk_bf16_f32 v113, v114, v115
	global_store_dwordx2 v[240:241], v[112:113], off offset:64
	v_pk_mul_f32 v[116:117], v[52:53], v[0:1] op_sel_hi:[1,0]
	v_pk_mul_f32 v[118:119], v[54:55], v[0:1] op_sel_hi:[1,0]
	v_pk_mul_f32 v[116:117], v[84:85], v[116:117]
	v_pk_mul_f32 v[118:119], v[86:87], v[118:119]
	v_cvt_pk_bf16_f32 v116, v116, v117
	v_cvt_pk_bf16_f32 v117, v118, v119
	global_store_dwordx2 v[240:241], v[116:117], off offset:80
	v_pk_mul_f32 v[120:121], v[56:57], v[0:1] op_sel_hi:[1,0]
	v_pk_mul_f32 v[122:123], v[58:59], v[0:1] op_sel_hi:[1,0]
	v_pk_mul_f32 v[120:121], v[88:89], v[120:121]
	v_pk_mul_f32 v[122:123], v[90:91], v[122:123]
	v_cvt_pk_bf16_f32 v120, v120, v121
	v_cvt_pk_bf16_f32 v121, v122, v123
	global_store_dwordx2 v[240:241], v[120:121], off offset:96
	v_pk_mul_f32 v[124:125], v[60:61], v[0:1] op_sel_hi:[1,0]
	v_pk_mul_f32 v[126:127], v[62:63], v[0:1] op_sel_hi:[1,0]
	v_pk_mul_f32 v[124:125], v[92:93], v[124:125]
	v_pk_mul_f32 v[126:127], v[94:95], v[126:127]
	v_cvt_pk_bf16_f32 v124, v124, v125
	v_cvt_pk_bf16_f32 v125, v126, v127
	global_store_dwordx2 v[240:241], v[124:125], off offset:112
	ds_read_b128 v[80:83], v7 offset:384
	ds_read_b128 v[84:87], v7 offset:416
	ds_read_b128 v[88:91], v7 offset:448
	ds_read_b128 v[92:95], v7 offset:480
	s_waitcnt lgkmcnt(4)
	v_pk_mul_f32 v[112:113], v[32:33], v[0:1] op_sel_hi:[1,0]
	v_pk_mul_f32 v[114:115], v[34:35], v[0:1] op_sel_hi:[1,0]
	v_pk_mul_f32 v[112:113], v[96:97], v[112:113]
	v_pk_mul_f32 v[114:115], v[98:99], v[114:115]
	v_cvt_pk_bf16_f32 v112, v112, v113
	v_cvt_pk_bf16_f32 v113, v114, v115
	global_store_dwordx2 v[240:241], v[112:113], off offset:128
	v_pk_mul_f32 v[116:117], v[36:37], v[0:1] op_sel_hi:[1,0]
	v_pk_mul_f32 v[118:119], v[38:39], v[0:1] op_sel_hi:[1,0]
	v_pk_mul_f32 v[116:117], v[100:101], v[116:117]
	v_pk_mul_f32 v[118:119], v[102:103], v[118:119]
	v_cvt_pk_bf16_f32 v116, v116, v117
	v_cvt_pk_bf16_f32 v117, v118, v119
	global_store_dwordx2 v[240:241], v[116:117], off offset:144
	v_pk_mul_f32 v[120:121], v[40:41], v[0:1] op_sel_hi:[1,0]
	v_pk_mul_f32 v[122:123], v[42:43], v[0:1] op_sel_hi:[1,0]
	v_pk_mul_f32 v[120:121], v[104:105], v[120:121]
	v_pk_mul_f32 v[122:123], v[106:107], v[122:123]
	v_cvt_pk_bf16_f32 v120, v120, v121
	v_cvt_pk_bf16_f32 v121, v122, v123
	global_store_dwordx2 v[240:241], v[120:121], off offset:160
	v_pk_mul_f32 v[124:125], v[44:45], v[0:1] op_sel_hi:[1,0]
	v_pk_mul_f32 v[126:127], v[46:47], v[0:1] op_sel_hi:[1,0]
	v_pk_mul_f32 v[124:125], v[108:109], v[124:125]
	v_pk_mul_f32 v[126:127], v[110:111], v[126:127]
	v_cvt_pk_bf16_f32 v124, v124, v125
	v_cvt_pk_bf16_f32 v125, v126, v127
	global_store_dwordx2 v[240:241], v[124:125], off offset:176
	s_waitcnt lgkmcnt(0)
	v_pk_mul_f32 v[112:113], v[16:17], v[0:1] op_sel_hi:[1,0]
	v_pk_mul_f32 v[114:115], v[18:19], v[0:1] op_sel_hi:[1,0]
	v_pk_mul_f32 v[112:113], v[80:81], v[112:113]
	v_pk_mul_f32 v[114:115], v[82:83], v[114:115]
	v_cvt_pk_bf16_f32 v112, v112, v113
	v_cvt_pk_bf16_f32 v113, v114, v115
	global_store_dwordx2 v[240:241], v[112:113], off offset:192
	v_pk_mul_f32 v[116:117], v[20:21], v[0:1] op_sel_hi:[1,0]
	v_pk_mul_f32 v[118:119], v[22:23], v[0:1] op_sel_hi:[1,0]
	v_pk_mul_f32 v[116:117], v[84:85], v[116:117]
	v_pk_mul_f32 v[118:119], v[86:87], v[118:119]
	v_cvt_pk_bf16_f32 v116, v116, v117
	v_cvt_pk_bf16_f32 v117, v118, v119
	global_store_dwordx2 v[240:241], v[116:117], off offset:208
	v_pk_mul_f32 v[120:121], v[24:25], v[0:1] op_sel_hi:[1,0]
	v_pk_mul_f32 v[122:123], v[26:27], v[0:1] op_sel_hi:[1,0]
	v_pk_mul_f32 v[120:121], v[88:89], v[120:121]
	v_pk_mul_f32 v[122:123], v[90:91], v[122:123]
	v_cvt_pk_bf16_f32 v120, v120, v121
	v_cvt_pk_bf16_f32 v121, v122, v123
	global_store_dwordx2 v[240:241], v[120:121], off offset:224
	v_pk_mul_f32 v[124:125], v[28:29], v[0:1] op_sel_hi:[1,0]
	v_pk_mul_f32 v[126:127], v[30:31], v[0:1] op_sel_hi:[1,0]
	v_pk_mul_f32 v[124:125], v[92:93], v[124:125]
	v_pk_mul_f32 v[126:127], v[94:95], v[126:127]
	v_cvt_pk_bf16_f32 v124, v124, v125
	v_cvt_pk_bf16_f32 v125, v126, v127
	global_store_dwordx2 v[240:241], v[124:125], off offset:240
.Ldf_c2_done:
	s_barrier
	s_cmp_eq_u32 s43, 8
	s_cbranch_scc1 .LBB0_210
	s_branch .Ldf_p2

; #define LAS __attribute__((address_space(3)))
; __global__ void __launch_bounds__(512, 2) fwd_kernel(Params P) {
;     extern __shared__ __attribute__((aligned(16))) unsigned char lds_raw[];
;     LAS unsigned char* lds = (LAS unsigned char*)lds_raw;
	.amdhsa_kernel _Z10fwd_kernel6Params
		.amdhsa_group_segment_fixed_size 512
		.amdhsa_private_segment_fixed_size 0
		.amdhsa_kernarg_size 440
		.amdhsa_user_sgpr_count 2
		.amdhsa_user_sgpr_dispatch_ptr 0
		.amdhsa_user_sgpr_queue_ptr 0
		.amdhsa_user_sgpr_kernarg_segment_ptr 1
		.amdhsa_user_sgpr_dispatch_id 0
		.amdhsa_user_sgpr_kernarg_preload_length 0
		.amdhsa_user_sgpr_kernarg_preload_offset 0
		.amdhsa_user_sgpr_private_segment_size 0
		.amdhsa_uses_dynamic_stack 0
		.amdhsa_enable_private_segment 0
		.amdhsa_system_sgpr_workgroup_id_x 1
		.amdhsa_system_sgpr_workgroup_id_y 0
		.amdhsa_system_sgpr_workgroup_id_z 0
		.amdhsa_system_sgpr_workgroup_info 0
		.amdhsa_system_vgpr_workitem_id 2
		.amdhsa_next_free_vgpr 255
		.amdhsa_next_free_sgpr 102
		.amdhsa_accum_offset 256
		.amdhsa_reserve_vcc 1
		.amdhsa_float_round_mode_32 0
		.amdhsa_float_round_mode_16_64 0
		.amdhsa_float_denorm_mode_32 3
		.amdhsa_float_denorm_mode_16_64 3
		.amdhsa_dx10_clamp 1
		.amdhsa_ieee_mode 1
		.amdhsa_fp16_overflow 0
		.amdhsa_tg_split 0
		.amdhsa_exception_fp_ieee_invalid_op 0
		.amdhsa_exception_fp_denorm_src 0
		.amdhsa_exception_fp_ieee_div_zero 0
		.amdhsa_exception_fp_ieee_overflow 0
		.amdhsa_exception_fp_ieee_underflow 0
		.amdhsa_exception_fp_ieee_inexact 0
		.amdhsa_exception_int_div_zero 0
	.end_amdhsa_kernel

; #define LAS __attribute__((address_space(3)))
; __global__ void __launch_bounds__(512, 2) fwd_kernel(Params P) {
;     extern __shared__ __attribute__((aligned(16))) unsigned char lds_raw[];
;     LAS unsigned char* lds = (LAS unsigned char*)lds_raw;
amdhsa.kernels:
  - .agpr_count:     0
    .args:
      - .offset:         0
        .size:           184
        .value_kind:     by_value
      - .offset:         184
        .size:           4
        .value_kind:     hidden_block_count_x
      - .offset:         188
        .size:           4
        .value_kind:     hidden_block_count_y
      - .offset:         192
        .size:           4
        .value_kind:     hidden_block_count_z
      - .offset:         196
        .size:           2
        .value_kind:     hidden_group_size_x
      - .offset:         198
        .size:           2
        .value_kind:     hidden_group_size_y
      - .offset:         200
        .size:           2
        .value_kind:     hidden_group_size_z
      - .offset:         202
        .size:           2
        .value_kind:     hidden_remainder_x
      - .offset:         204
        .size:           2
        .value_kind:     hidden_remainder_y
      - .offset:         206
        .size:           2
        .value_kind:     hidden_remainder_z
      - .offset:         224
        .size:           8
        .value_kind:     hidden_global_offset_x
      - .offset:         232
        .size:           8
        .value_kind:     hidden_global_offset_y
      - .offset:         240
        .size:           8
        .value_kind:     hidden_global_offset_z
      - .offset:         248
        .size:           2
        .value_kind:     hidden_grid_dims
      - .offset:         272
        .size:           8
        .value_kind:     hidden_multigrid_sync_arg
      - .offset:         304
        .size:           4
        .value_kind:     hidden_dynamic_lds_size
    .group_segment_fixed_size: 512
    .kernarg_segment_align: 8
    .kernarg_segment_size: 440
    .language:       OpenCL C
    .language_version:
      - 2
      - 0
    .max_flat_workgroup_size: 512
    .name:           _Z10fwd_kernel6Params
    .private_segment_fixed_size: 0
    .sgpr_count:     108
    .sgpr_spill_count: 10
    .symbol:         _Z10fwd_kernel6Params.kd
    .uniform_work_group_size: 1
    .uses_dynamic_stack: false
    .vgpr_count:     255
    .vgpr_spill_count: 0
    .wavefront_size: 64
